# P0 rmsnorm loop top: counted vmcnt wait sunk below the next-row address math
# speedup vs baseline: 1.0058x; 1.0058x over previous
; DI void rmsnorm_rows(const float* src, const float* w, u16* dst, const float* wabT, float* ab, int bid, int nb) {
;     ...
;     const float4* xr = (const float4*)(src + (size_t)row * 1024);
;     float4 v[4]; float ss = 0.f;
; #pragma unroll
;     for (int i = 0; i < 4; i++) { v[i] = xr[lane + 64 * i]; ss += v[i].x * v[i].x + v[i].y * v[i].y + v[i].z * v[i].z + v[i].w * v[i].w; }
;     ss = wsum(ss);
;     const float rstd = rsqrtf(ss * (1.f / 1024.f) + EPSF);
;     float acc[8];
; #pragma unroll
;     for (int j = 0; j < 8; j++) acc[j] = 0.f;
; #pragma unroll
;     for (int i = 0; i < 4; i++) {
;       const int k0 = (lane + 64 * i) * 4;
;       float4 ww = *(const float4*)(w + k0);
;       float y0 = v[i].x * rstd * ww.x, y1 = v[i].y * rstd * ww.y, y2 = v[i].z * rstd * ww.z, y3 = v[i].w * rstd * ww.w;
;       u32x2 pk; pk.x = pack2(y0, y1); pk.y = pack2(y2, y3);
;       *(u32x2*)(dst + (size_t)row * 1024 + k0) = pk;
;       if (wabT) {
; #pragma unroll
;         for (int j = 0; j < 8; j++) {
;           float4 wj = *(const float4*)(wabT + j * 1024 + k0);
;           acc[j] += y0 * wj.x + y1 * wj.y + y2 * wj.z + y3 * wj.w;
;         }
;       }
.LBB0_20:
	v_add_u32_e32 v134, s8, v26
	v_lshl_add_u64 v[132:133], v[32:33], 0, s[10:11]
	v_cmp_gt_i32_e32 vcc, 0x4000, v134
	s_nop 0
	v_cndmask_b32_e32 v132, v32, v132, vcc
	v_cndmask_b32_e32 v133, v33, v133, vcc
	s_waitcnt vmcnt(4)
	v_mov_b32_e32 v20, v116
	v_mov_b32_e32 v21, v117
	v_mov_b32_e32 v22, v118
	v_mov_b32_e32 v23, v119
	global_load_dwordx4 v[116:119], v[132:133], off offset:-1024
	s_waitcnt lgkmcnt(0)
	v_mov_b32_e32 v16, v120
	v_mov_b32_e32 v17, v121
	v_mov_b32_e32 v18, v122
	v_mov_b32_e32 v19, v123
	global_load_dwordx4 v[120:123], v[132:133], off
	v_mov_b32_e32 v12, v124
	v_mov_b32_e32 v13, v125
	v_mov_b32_e32 v14, v126
	v_mov_b32_e32 v15, v127
	global_load_dwordx4 v[124:127], v[132:133], off offset:1024
	s_mov_b32 s3, 0x800000
	v_mov_b32_e32 v51, v21
	v_mov_b32_e32 v6, v17
	v_mov_b32_e32 v7, v13
	v_mov_b32_e32 v4, v16
	v_mov_b32_e32 v5, v12
	v_pk_mul_f32 v[6:7], v[6:7], v[6:7]
	v_mov_b32_e32 v49, v20
	v_pk_fma_f32 v[4:5], v[4:5], v[4:5], v[6:7]
	v_mov_b32_e32 v6, v18
	v_mov_b32_e32 v7, v14
	v_pk_fma_f32 v[4:5], v[6:7], v[6:7], v[4:5]
	v_mov_b32_e32 v6, v19
	v_mov_b32_e32 v7, v15
	v_pk_fma_f32 v[38:39], v[6:7], v[6:7], v[4:5]
	v_mov_b32_e32 v4, v128
	v_mov_b32_e32 v5, v129
	v_mov_b32_e32 v6, v130
	v_mov_b32_e32 v7, v131
	global_load_dwordx4 v[128:131], v[132:133], off offset:-2048
	v_mov_b32_e32 v8, v100
	v_mov_b32_e32 v9, v101
	v_mov_b32_e32 v10, v102
	v_mov_b32_e32 v11, v103
	v_mov_b32_e32 v45, v22
	v_mov_b32_e32 v47, v23
	v_mov_b32_e32 v50, v5
	v_mov_b32_e32 v48, v4
	v_pk_mul_f32 v[50:51], v[50:51], v[50:51]
	v_mov_b32_e32 v44, v6
	v_pk_fma_f32 v[48:49], v[48:49], v[48:49], v[50:51]
	v_mov_b32_e32 v46, v7
	v_pk_fma_f32 v[44:45], v[44:45], v[44:45], v[48:49]
	s_nop 0
	v_pk_fma_f32 v[44:45], v[46:47], v[46:47], v[44:45]
	s_nop 0
	v_add_f32_e32 v3, v44, v45
	v_add_f32_e32 v3, v3, v38
	v_add_f32_e32 v3, v3, v39
	ds_bpermute_b32 v29, v1, v3
	s_waitcnt lgkmcnt(0)
	v_add_f32_e32 v3, v3, v29
	ds_bpermute_b32 v29, v25, v3
	s_waitcnt lgkmcnt(0)
	v_add_f32_e32 v3, v3, v29
	ds_bpermute_b32 v29, v40, v3
	s_waitcnt lgkmcnt(0)
	v_add_f32_e32 v3, v3, v29
	ds_bpermute_b32 v29, v41, v3
	s_waitcnt lgkmcnt(0)
	v_add_f32_e32 v3, v3, v29
	ds_bpermute_b32 v29, v42, v3
	s_waitcnt lgkmcnt(0)
	v_add_f32_e32 v3, v3, v29
	ds_bpermute_b32 v29, v43, v3
	s_waitcnt lgkmcnt(0)
	v_add_f32_e32 v3, v3, v29
	v_fmamk_f32 v3, v3, 0x3a800000, v27
	v_cmp_gt_f32_e32 vcc, s3, v3
	v_mul_f32_e32 v29, 0x4b800000, v3
	s_nop 0
	v_cndmask_b32_e32 v3, v3, v29, vcc
	v_rsq_f32_e32 v3, v3
	s_nop 0
	v_mul_f32_e32 v29, 0x45800000, v3
	v_cndmask_b32_e32 v38, v3, v29, vcc
	v_pk_mul_f32 v[4:5], v[4:5], v[38:39] op_sel_hi:[1,0]
	v_pk_mul_f32 v[6:7], v[6:7], v[38:39] op_sel_hi:[1,0]
	v_pk_mul_f32 v[4:5], v[8:9], v[4:5]
	v_pk_mul_f32 v[6:7], v[10:11], v[6:7]
	v_cvt_pk_bf16_f32 v8, v4, v5
	v_cvt_pk_bf16_f32 v9, v6, v7
	s_and_b64 vcc, exec, s[4:5]
	global_store_dwordx2 v[36:37], v[8:9], off offset:-1024
	s_cbranch_vccnz .LBB0_22
	ds_read_b128 v[8:11], v28 offset:256
	ds_read_b128 v[44:47], v28 offset:4352
	ds_read_b128 v[48:51], v28 offset:8448
	ds_read_b128 v[52:55], v28 offset:12544
	s_waitcnt lgkmcnt(3)
	v_mov_b32_e32 v62, v10
	s_waitcnt lgkmcnt(2)
	v_pk_mov_b32 v[60:61], v[8:9], v[44:45] op_sel:[1,0]
	v_mov_b32_e32 v9, v45
	v_pk_mul_f32 v[44:45], v[4:5], v[8:9]
	v_mov_b32_e32 v63, v46
	v_mov_b32_e32 v46, v11
	ds_read_b128 v[8:11], v28 offset:16640
	ds_read_b128 v[56:59], v28 offset:20736
	s_waitcnt lgkmcnt(2)
	v_pk_mov_b32 v[64:65], v[48:49], v[52:53] op_sel:[1,0]
	v_mov_b32_e32 v49, v53
	v_pk_mul_f32 v[52:53], v[4:5], v[48:49]
	v_mov_b32_e32 v66, v50
	s_waitcnt lgkmcnt(0)
	v_pk_mov_b32 v[68:69], v[8:9], v[56:57] op_sel:[1,0]
	v_mov_b32_e32 v9, v57
	v_mov_b32_e32 v67, v54
	v_mov_b32_e32 v54, v51
	v_pk_mul_f32 v[56:57], v[4:5], v[8:9]
	ds_read_b128 v[48:51], v28 offset:24832
	v_mov_b32_e32 v70, v10
	v_mov_b32_e32 v71, v58
	v_mov_b32_e32 v58, v11
	ds_read_b128 v[8:11], v28 offset:28928
	s_waitcnt lgkmcnt(1)
	v_mul_f32_e32 v48, v4, v48
	v_mul_f32_e32 v72, v5, v49
	v_mul_f32_e32 v50, v6, v50
	v_mul_f32_e32 v74, v7, v51
	s_waitcnt lgkmcnt(0)
	v_pk_mul_f32 v[8:9], v[4:5], v[8:9]
	v_pk_mul_f32 v[10:11], v[6:7], v[10:11]
	v_mov_b32_e32 v49, v8
	v_mov_b32_e32 v73, v9
	v_mov_b32_e32 v51, v10
	v_mov_b32_e32 v75, v11
	v_pk_fma_f32 v[8:9], v[4:5], v[60:61], v[44:45] op_sel:[1,0,0] op_sel_hi:[0,1,1]
	v_pk_fma_f32 v[10:11], v[4:5], v[64:65], v[52:53] op_sel:[1,0,0] op_sel_hi:[0,1,1]
	v_pk_fma_f32 v[4:5], v[4:5], v[68:69], v[56:57] op_sel:[1,0,0] op_sel_hi:[0,1,1]
	v_pk_add_f32 v[44:45], v[48:49], v[72:73]
	v_pk_fma_f32 v[8:9], v[6:7], v[62:63], v[8:9] op_sel_hi:[0,1,1]
	v_pk_fma_f32 v[10:11], v[6:7], v[66:67], v[10:11] op_sel_hi:[0,1,1]
	v_pk_fma_f32 v[4:5], v[6:7], v[70:71], v[4:5] op_sel_hi:[0,1,1]
	v_pk_add_f32 v[44:45], v[44:45], v[50:51]
	v_pk_fma_f32 v[46:47], v[6:7], v[46:47], v[8:9] op_sel:[1,0,0]
	v_pk_fma_f32 v[10:11], v[6:7], v[54:55], v[10:11] op_sel:[1,0,0]
	v_pk_fma_f32 v[4:5], v[6:7], v[58:59], v[4:5] op_sel:[1,0,0]
	v_pk_add_f32 v[44:45], v[44:45], v[74:75]
	v_pk_add_f32 v[8:9], v[4:5], 0 op_sel_hi:[1,0]
	v_pk_add_f32 v[6:7], v[10:11], 0 op_sel_hi:[1,0]
	v_pk_add_f32 v[4:5], v[46:47], 0 op_sel_hi:[1,0]
	v_pk_add_f32 v[10:11], v[44:45], 0 op_sel_hi:[1,0]
	s_branch .LBB0_23
